# previous best plus LRU pass-B clean-up: gate-side loads via d16_hi into dedicated registers issued behind the step barrier (no unpack shifts, no per-load address pairs), one running pointer for the ou
# speedup vs baseline: 1.0067x; 1.0058x over previous
; template <bool PASSB>
; __device__ __forceinline__ void lru_unit(LAS unsigned char* lds, const Params& p, int b, int hd, int chunk) {
;     ...
;     const float brv = p.in[9][gch], biv = p.in[11][gch];
;     float clv; { const float L = p.in[12][gch]; clv = -8.0f * (fmaxf(-L, 0.f) + log1pf(expf(-fabsf(L)))); }
;     const int ch8 = (tid & 15) * 8, tok = tid >> 4;
;     float Cst = 0.f, Pacc = 1.f;
;     if (PASSB) {
;         f32x2 e[LRU_NC];
; #pragma unroll
;         for (int j = 0; j < LRU_NC - 1; ++j) { const int jj = j < chunk ? j : 0; e[j] = *(const f32x2*)(AGG + ((size_t)(b * LRU_NC + jj) * 1024 + gch) * 2); }
; #pragma unroll
;         for (int j = 0; j < LRU_NC - 1; ++j) if (j < chunk) Cst = e[j][0] * Cst + e[j][1];
;     }
;     f32x4 cw0[4], cw1[4];
; #pragma unroll
;     for (int k = 0; k < 4; ++k) { cw0[k] = *(const f32x4*)(p.in[6] + k * 1024 + hd * 128 + ch8); cw1[k] = *(const f32x4*)(p.in[6] + k * 1024 + hd * 128 + ch8 + 4); }
;     const f32x4 cb0 = *(const f32x4*)(p.in[7] + hd * 128 + ch8), cb1 = *(const f32x4*)(p.in[7] + hd * 128 + ch8 + 4);
;     u32x4 xw[2][4];
;     const bf16_t* xbase = XA + ((size_t)b * SEQ) * 1024 + hd * 128 + ch8;
.LBB0_598:
	s_or_b64 exec, exec, s[60:61]
	s_waitcnt vmcnt(15)
	v_fmac_f32_e32 v125, v124, v129
	v_cndmask_b32_e64 v112, v129, v125, s[0:1]
	s_waitcnt vmcnt(14)
	v_fmac_f32_e32 v109, v108, v112
	v_cndmask_b32_e64 v108, v112, v109, s[14:15]
	s_waitcnt vmcnt(13)
	v_fmac_f32_e32 v107, v106, v108
	v_cndmask_b32_e64 v106, v108, v107, s[4:5]
	s_waitcnt vmcnt(12)
	v_fmac_f32_e32 v105, v104, v106
	v_cndmask_b32_e64 v104, v106, v105, s[8:9]
	v_mul_f32_e64 v105, |v117|, s62
	v_rndne_f32_e32 v106, v105
	v_sub_f32_e32 v107, v105, v106
	v_fma_f32 v105, |v117|, s62, -v105
	s_mov_b32 s0, 0xb2a5705f
	v_fma_f32 v105, |v117|, s0, v105
	v_add_f32_e32 v105, v107, v105
	s_waitcnt vmcnt(11)
	v_fmac_f32_e32 v127, v126, v104
	v_exp_f32_e32 v105, v105
	v_cvt_i32_f32_e32 v106, v106
	v_cndmask_b32_e64 v104, v104, v127, s[12:13]
	s_waitcnt vmcnt(10)
	v_fmac_f32_e32 v111, v110, v104
	v_cndmask_b32_e64 v137, v104, v111, s[10:11]
	v_max_f32_e64 v104, -v117, -v117
	s_mov_b32 s0, 0x42ce8ed0
	v_max_f32_e32 v107, 0, v104
	v_ldexp_f32 v104, v105, v106
	v_cmp_ngt_f32_e64 vcc, |v117|, s0
	s_mov_b32 s0, 0xc2b17218
	s_lshl_b64 s[4:5], s[58:59], 13
	v_cndmask_b32_e32 v104, 0, v104, vcc
	v_cmp_nlt_f32_e64 vcc, |v117|, s0
	s_mov_b32 s0, 0x3f2aaaab
	s_ashr_i32 s9, s83, 31
	v_cndmask_b32_e32 v106, v134, v104, vcc
	v_add_f32_e32 v108, 1.0, v106
	v_add_f32_e32 v104, -1.0, v108
	v_sub_f32_e32 v105, v104, v108
	v_add_f32_e32 v105, 1.0, v105
	v_sub_f32_e32 v104, v106, v104
	v_add_f32_e32 v109, v104, v105
	v_frexp_mant_f32_e32 v110, v108
	v_cvt_f64_f32_e32 v[104:105], v108
	v_frexp_exp_i32_f64_e32 v104, v[104:105]
	v_cmp_gt_f32_e32 vcc, s0, v110
	s_mov_b32 s0, 0x3f317218
	s_add_u32 s8, s83, s4
	v_subbrev_co_u32_e32 v104, vcc, 0, v104, vcc
	v_sub_u32_e32 v105, 0, v104
	v_ldexp_f32 v108, v108, v105
	v_ldexp_f32 v105, v109, v105
	v_add_f32_e32 v109, -1.0, v108
	v_add_f32_e32 v112, 1.0, v108
	v_add_f32_e32 v110, 1.0, v109
	v_add_f32_e32 v117, -1.0, v112
	v_sub_f32_e32 v110, v108, v110
	v_sub_f32_e32 v108, v108, v117
	v_add_f32_e32 v110, v105, v110
	v_add_f32_e32 v105, v105, v108
	v_add_f32_e32 v108, v112, v105
	v_rcp_f32_e32 v117, v108
	v_add_f32_e32 v111, v109, v110
	v_sub_f32_e32 v109, v109, v111
	v_add_f32_e32 v109, v110, v109
	v_sub_f32_e32 v110, v112, v108
	v_add_f32_e32 v105, v105, v110
	v_mul_f32_e32 v110, v111, v117
	v_mul_f32_e32 v112, v108, v110
	v_fma_f32 v119, v110, v108, -v112
	v_fmac_f32_e32 v119, v110, v105
	v_add_f32_e32 v121, v112, v119
	v_sub_f32_e32 v124, v111, v121
	v_sub_f32_e32 v111, v111, v124
	v_sub_f32_e32 v112, v121, v112
	v_sub_f32_e32 v111, v111, v121
	v_add_f32_e32 v109, v109, v111
	v_sub_f32_e32 v111, v112, v119
	v_add_f32_e32 v109, v111, v109
	v_add_f32_e32 v111, v124, v109
	v_mul_f32_e32 v112, v117, v111
	v_mul_f32_e32 v119, v108, v112
	v_fma_f32 v108, v112, v108, -v119
	v_fmac_f32_e32 v108, v112, v105
	v_sub_f32_e32 v105, v124, v111
	v_add_f32_e32 v105, v109, v105
	v_add_f32_e32 v109, v119, v108
	v_sub_f32_e32 v121, v111, v109
	v_sub_f32_e32 v111, v111, v121
	v_sub_f32_e32 v119, v109, v119
	v_sub_f32_e32 v109, v111, v109
	v_add_f32_e32 v105, v105, v109
	v_sub_f32_e32 v108, v119, v108
	v_cvt_f32_i32_e32 v104, v104
	v_add_f32_e32 v105, v108, v105
	v_add_f32_e32 v108, v110, v112
	v_add_f32_e32 v105, v121, v105
	v_sub_f32_e32 v109, v108, v110
	v_mul_f32_e32 v105, v117, v105
	v_sub_f32_e32 v109, v112, v109
	v_add_f32_e32 v105, v109, v105
	v_mul_f32_e32 v112, 0x3f317218, v104
	v_add_f32_e32 v109, v108, v105
	v_fma_f32 v117, v104, s0, -v112
	v_mul_f32_e32 v110, v109, v109
	v_fmac_f32_e32 v117, 0xb102e308, v104
	v_sub_f32_e32 v104, v109, v108
	v_fmamk_f32 v111, v110, 0x3e9b6dac, v132
	v_sub_f32_e32 v104, v105, v104
	v_add_f32_e32 v105, v112, v117
	v_fmaak_f32 v111, v110, v111, 0x3f2aaada
	v_sub_f32_e32 v108, v105, v112
	v_ldexp_f32 v112, v109, 1
	v_mul_f32_e32 v109, v109, v110
	v_mul_f32_e32 v109, v109, v111
	v_add_f32_e32 v110, v112, v109
	v_sub_f32_e32 v111, v110, v112
	v_ldexp_f32 v104, v104, 1
	v_sub_f32_e32 v109, v109, v111
	v_add_f32_e32 v104, v104, v109
	v_add_f32_e32 v109, v110, v104
	v_sub_f32_e32 v110, v109, v110
	v_sub_f32_e32 v104, v104, v110
	v_add_f32_e32 v110, v105, v109
	v_sub_f32_e32 v111, v110, v105
	v_sub_f32_e32 v112, v110, v111
	v_sub_f32_e32 v108, v117, v108
	v_sub_f32_e32 v105, v105, v112
	v_sub_f32_e32 v109, v109, v111
	v_add_f32_e32 v105, v109, v105
	v_add_f32_e32 v109, v108, v104
	v_sub_f32_e32 v111, v109, v108
	v_sub_f32_e32 v112, v109, v111
	v_sub_f32_e32 v108, v108, v112
	v_sub_f32_e32 v104, v104, v111
	v_add_f32_e32 v105, v109, v105
	v_add_f32_e32 v104, v104, v108
	v_add_f32_e32 v108, v110, v105
	v_sub_f32_e32 v109, v108, v110
	v_sub_f32_e32 v105, v105, v109
	v_add_f32_e32 v104, v104, v105
	s_mov_b32 s0, 0x7f800000
	v_add_f32_e32 v104, v108, v104
	v_cmp_neq_f32_e32 vcc, s0, v106
	v_ashrrev_i32_e32 v105, 6, v138
	v_and_b32_e32 v105, 0xffffffc, v105
	v_cndmask_b32_e32 v104, v134, v104, vcc
	v_cmp_lt_f32_e64 vcc, |v106|, s63
	v_mov_b32_e32 v117, v113
	s_addc_u32 s9, s9, s5
	v_cndmask_b32_e32 v104, v104, v106, vcc
	v_add_f32_e32 v104, v107, v104
	v_mul_f32_e32 v119, 0xc1000000, v104
	v_lshrrev_b32_e32 v104, 2, v138
	v_and_or_b32 v104, v104, 48, v135
	v_add_u32_e32 v105, v104, v105
	v_mul_lo_u32 v139, v105, s64
	v_add_u32_e32 v105, 32, v128
	v_lshrrev_b32_e32 v105, 2, v105
	v_and_b32_e32 v105, 0xffffffc, v105
	v_add_u32_e32 v104, v105, v104
	v_mul_lo_u32 v131, v104, s64
	v_lshl_add_u64 v[104:105], s[8:9], 0, v[116:117]
	v_lshlrev_b64 v[104:105], 10, v[104:105]
	v_add_u32_e32 v106, v141, v140
	v_or_b32_e32 v104, s56, v104
	v_ashrrev_i32_e32 v107, 31, v106
	v_lshl_add_u64 v[104:105], v[104:105], 0, v[106:107]
	v_lshl_add_u64 v[124:125], v[104:105], 1, s[78:79]
	v_lshl_add_u32 v104, s82, 10, v128
	s_lshl_b32 s8, s28, 13
	v_subrev_u32_e32 v104, s8, v104
	v_add_u32_e32 v126, 0x60, v104
	v_and_or_b32 v104, v133, 64, v140
	s_mov_b32 s14, 0
	v_cmp_eq_u32_e64 s[0:1], 2, v135
	v_mul_lo_u32 v138, v128, s65
	v_mul_u32_u24_e32 v130, 0x110, v140
	v_mul_u32_u24_e32 v121, 0x2100, v135
	s_mov_b64 s[8:9], 0
	v_lshlrev_b32_e32 v117, 2, v104
	s_mov_b32 s72, 0xbfb8aa3b
	s_mov_b32 s73, 0x4266d4ca
	v_mul_f32_e32 v200, s72, v136
	v_mul_f32_e32 v201, s72, v115
	v_mul_f32_e32 v202, 0x3fb8aa3b, v119
	v_mov_b32_e32 v204, 0
	v_mov_b32_e32 v205, 0
	v_mov_b32_e32 v206, 0
	v_mov_b32_e32 v207, 0
	v_mov_b32_e32 v208, 0
	v_mov_b32_e32 v209, 0
	v_mov_b32_e32 v210, 0
	v_mov_b32_e32 v211, 0
	v_mov_b32_e32 v212, 0
	v_mov_b32_e32 v213, 0
	v_mov_b32_e32 v214, 0
	v_mov_b32_e32 v215, 0
	v_mov_b32_e32 v216, 0
	v_mov_b32_e32 v217, 0
	v_mov_b32_e32 v218, 0
	v_mov_b32_e32 v219, 0
	s_mov_b32 s86, 0xe000000
	s_mov_b32 s87, 0
	s_mov_b32 s88, 0x1000
	s_mov_b32 s89, 0
	s_waitcnt vmcnt(0)
; #define LAS __attribute__((address_space(3)))
; __device__ __forceinline__ unsigned cvt_pk_bf16(float lo, float hi) { unsigned r; asm volatile("v_cvt_pk_bf16_f32 %0, %1, %2" : "=v"(r) : "v"(lo), "v"(hi)); return r; }
; __device__ __forceinline__ float bflo(unsigned w) { return __uint_as_float(w << 16); }
; __device__ __forceinline__ float bfhi(unsigned w) { return __uint_as_float(w & 0xffff0000u); }
; #define LRU_LOADX(st_) do { const int t0_ = chunk * LRU_LC + (st_) * 64; _Pragma("unroll") for (int i_ = 0; i_ < 2; ++i_) _Pragma("unroll") for (int k_ = 0; k_ < 4; ++k_) { \
;         const int ts_ = t0_ + tok + 32 * i_ - 3 + k_; xw[i_][k_] = (ts_ >= 0) ? *(const u32x4*)(xbase + (size_t)ts_ * 1024) : (u32x4){0u, 0u, 0u, 0u}; } } while (0)
; template <bool PASSB>
; __device__ __forceinline__ void lru_unit(LAS unsigned char* lds, const Params& p, int b, int hd, int chunk) {
;     ...
; #pragma unroll
;         for (int i = 0; i < 2; ++i) {
;             const int token = tok + 32 * i;
;             f32x4 a0 = cb0, a1 = cb1;
; #pragma unroll
;             for (int k = 0; k < 4; ++k) {
;                 const u32x4 x4 = xw[i][k];
;                 a0[0] += cw0[k][0] * bflo(x4.x); a0[1] += cw0[k][1] * bfhi(x4.x); a0[2] += cw0[k][2] * bflo(x4.y); a0[3] += cw0[k][3] * bfhi(x4.y);
;                 a1[0] += cw1[k][0] * bflo(x4.z); a1[1] += cw1[k][1] * bfhi(x4.z); a1[2] += cw1[k][2] * bflo(x4.w); a1[3] += cw1[k][3] * bfhi(x4.w);
;             }
;             u32x4 w; w.x = cvt_pk_bf16(a0[0], a0[1]); w.y = cvt_pk_bf16(a0[2], a0[3]); w.z = cvt_pk_bf16(a1[0], a1[1]); w.w = cvt_pk_bf16(a1[2], a1[3]);
;             *(LAS u32x4*)(XCB + (((token >> 2) & 3) * 16 + (token >> 4) * 4 + (token & 3)) * 272 + ch8 * 2) = w;
;             *(LAS f32x4*)(XCF + token * 132 + ch8) = a0; *(LAS f32x4*)(XCF + token * 132 + ch8 + 4) = a1;
;         }
;         __syncthreads();
;         if (st + 1 < NST) LRU_LOADX(st + 1);
;         const size_t obase = ((size_t)b * SEQ + t0 + fq * 16) * 1024 + hd * 128 + chl;
;         unsigned short gvv[16];
;         if (PASSB) {
; #pragma unroll
;             for (int q = 0; q < 16; ++q) gvv[q] = GA[obase + (size_t)q * 1024];
;         }
.LBB0_599:
	s_waitcnt vmcnt(16)
	v_lshlrev_b32_e32 v104, 16, v72
	v_and_b32_e32 v105, 0xffff0000, v72
	v_lshlrev_b32_e32 v72, 16, v73
	v_and_b32_e32 v73, 0xffff0000, v73
	v_pk_fma_f32 v[104:105], v[52:53], v[104:105], v[68:69]
	v_lshlrev_b32_e32 v106, 16, v80
	v_and_b32_e32 v107, 0xffff0000, v80
	v_pk_fma_f32 v[72:73], v[54:55], v[72:73], v[70:71]
	v_lshlrev_b32_e32 v80, 16, v81
	v_and_b32_e32 v81, 0xffff0000, v81
	v_pk_fma_f32 v[104:105], v[56:57], v[106:107], v[104:105]
	v_lshlrev_b32_e32 v106, 16, v84
	v_and_b32_e32 v107, 0xffff0000, v84
	v_pk_fma_f32 v[72:73], v[58:59], v[80:81], v[72:73]
	v_lshlrev_b32_e32 v80, 16, v85
	v_and_b32_e32 v81, 0xffff0000, v85
	v_pk_fma_f32 v[104:105], v[60:61], v[106:107], v[104:105]
	v_lshlrev_b32_e32 v106, 16, v96
	v_and_b32_e32 v107, 0xffff0000, v96
	v_pk_fma_f32 v[72:73], v[62:63], v[80:81], v[72:73]
	v_lshlrev_b32_e32 v80, 16, v97
	v_and_b32_e32 v81, 0xffff0000, v97
	v_pk_fma_f32 v[104:105], v[64:65], v[106:107], v[104:105]
	v_pk_fma_f32 v[106:107], v[66:67], v[80:81], v[72:73]
	v_lshlrev_b32_e32 v72, 16, v74
	v_and_b32_e32 v73, 0xffff0000, v74
	v_pk_fma_f32 v[72:73], v[32:33], v[72:73], v[48:49]
	v_lshlrev_b32_e32 v80, 16, v82
	v_and_b32_e32 v81, 0xffff0000, v82
	s_bitcmp1_b32 s14, 0
	v_pk_fma_f32 v[72:73], v[36:37], v[80:81], v[72:73]
	v_lshlrev_b32_e32 v80, 16, v86
	v_and_b32_e32 v81, 0xffff0000, v86
	s_cselect_b32 s10, 0xc800, 0
	v_pk_fma_f32 v[72:73], v[40:41], v[80:81], v[72:73]
	v_lshlrev_b32_e32 v80, 16, v98
	v_and_b32_e32 v81, 0xffff0000, v98
	v_lshlrev_b32_e32 v74, 16, v75
	v_and_b32_e32 v75, 0xffff0000, v75
	s_add_i32 s12, s10, 0
	v_pk_fma_f32 v[72:73], v[44:45], v[80:81], v[72:73]
	v_pk_fma_f32 v[74:75], v[34:35], v[74:75], v[50:51]
	v_lshlrev_b32_e32 v80, 16, v83
	v_and_b32_e32 v81, 0xffff0000, v83
	v_add_u32_e32 v108, s12, v120
	v_pk_fma_f32 v[74:75], v[38:39], v[80:81], v[74:75]
	v_lshlrev_b32_e32 v80, 16, v87
	v_and_b32_e32 v81, 0xffff0000, v87
	v_pk_fma_f32 v[74:75], v[42:43], v[80:81], v[74:75]
	v_lshlrev_b32_e32 v80, 16, v99
	v_and_b32_e32 v81, 0xffff0000, v99
	v_add_u32_e32 v84, v108, v139
	v_pk_fma_f32 v[74:75], v[46:47], v[80:81], v[74:75]
	v_cvt_pk_bf16_f32 v80, v104, v105
	v_cvt_pk_bf16_f32 v81, v106, v107
	v_cvt_pk_bf16_f32 v82, v72, v73
	v_add_u32_e32 v85, v108, v131
	v_cvt_pk_bf16_f32 v83, v74, v75
	ds_write_b128 v84, v[80:83]
	v_add3_u32 v84, s12, v118, v138
	ds_write_b128 v84, v[104:107] offset:17408
	ds_write_b128 v84, v[72:75] offset:17424
	v_lshlrev_b32_e32 v72, 16, v76
	v_and_b32_e32 v73, 0xffff0000, v76
	v_pk_fma_f32 v[72:73], v[52:53], v[72:73], v[68:69]
	v_lshlrev_b32_e32 v74, 16, v88
	v_and_b32_e32 v75, 0xffff0000, v88
	v_pk_fma_f32 v[72:73], v[56:57], v[74:75], v[72:73]
	v_lshlrev_b32_e32 v74, 16, v92
	v_and_b32_e32 v75, 0xffff0000, v92
	v_pk_fma_f32 v[72:73], v[60:61], v[74:75], v[72:73]
	v_lshlrev_b32_e32 v74, 16, v100
	v_and_b32_e32 v75, 0xffff0000, v100
	v_pk_fma_f32 v[72:73], v[64:65], v[74:75], v[72:73]
	v_lshlrev_b32_e32 v74, 16, v77
	v_and_b32_e32 v75, 0xffff0000, v77
	v_pk_fma_f32 v[74:75], v[54:55], v[74:75], v[70:71]
	v_lshlrev_b32_e32 v76, 16, v89
	v_and_b32_e32 v77, 0xffff0000, v89
	v_pk_fma_f32 v[74:75], v[58:59], v[76:77], v[74:75]
	v_lshlrev_b32_e32 v76, 16, v93
	v_and_b32_e32 v77, 0xffff0000, v93
	v_pk_fma_f32 v[74:75], v[62:63], v[76:77], v[74:75]
	v_lshlrev_b32_e32 v76, 16, v101
	v_and_b32_e32 v77, 0xffff0000, v101
	v_pk_fma_f32 v[74:75], v[66:67], v[76:77], v[74:75]
	v_lshlrev_b32_e32 v76, 16, v78
	v_and_b32_e32 v77, 0xffff0000, v78
	v_pk_fma_f32 v[76:77], v[32:33], v[76:77], v[48:49]
	v_lshlrev_b32_e32 v80, 16, v90
	v_and_b32_e32 v81, 0xffff0000, v90
	v_pk_fma_f32 v[76:77], v[36:37], v[80:81], v[76:77]
	v_lshlrev_b32_e32 v80, 16, v94
	v_and_b32_e32 v81, 0xffff0000, v94
	v_pk_fma_f32 v[76:77], v[40:41], v[80:81], v[76:77]
	v_lshlrev_b32_e32 v80, 16, v102
	v_and_b32_e32 v81, 0xffff0000, v102
	v_lshlrev_b32_e32 v78, 16, v79
	v_and_b32_e32 v79, 0xffff0000, v79
	v_pk_fma_f32 v[76:77], v[44:45], v[80:81], v[76:77]
	v_pk_fma_f32 v[78:79], v[34:35], v[78:79], v[50:51]
	v_lshlrev_b32_e32 v80, 16, v91
	v_and_b32_e32 v81, 0xffff0000, v91
	v_pk_fma_f32 v[78:79], v[38:39], v[80:81], v[78:79]
	v_lshlrev_b32_e32 v80, 16, v95
	v_and_b32_e32 v81, 0xffff0000, v95
	v_pk_fma_f32 v[78:79], v[42:43], v[80:81], v[78:79]
	v_lshlrev_b32_e32 v80, 16, v103
	v_and_b32_e32 v81, 0xffff0000, v103
	v_pk_fma_f32 v[78:79], v[46:47], v[80:81], v[78:79]
	v_cvt_pk_bf16_f32 v80, v72, v73
	v_cvt_pk_bf16_f32 v81, v74, v75
	v_cvt_pk_bf16_f32 v82, v76, v77
	v_subrev_u32_e32 v112, 35, v126
	v_cvt_pk_bf16_f32 v83, v78, v79
	ds_write_b128 v85, v[80:83]
	ds_write_b128 v84, v[72:75] offset:34304
	ds_write_b128 v84, v[76:79] offset:34320
	s_waitcnt lgkmcnt(0)
	s_barrier
	s_add_u32 s90, s8, 0xa000000
	s_addc_u32 s91, s9, 0
	v_lshl_add_u64 v[220:221], v[124:125], 0, s[90:91]
	global_load_short_d16_hi v204, v[220:221], off
	global_load_short_d16_hi v205, v[220:221], off offset:2048
	s_add_u32 s90, s8, 0xa001000
	s_addc_u32 s91, s9, 0
	v_lshl_add_u64 v[220:221], v[124:125], 0, s[90:91]
	global_load_short_d16_hi v206, v[220:221], off
	global_load_short_d16_hi v207, v[220:221], off offset:2048
	s_add_u32 s90, s8, 0xa002000
	s_addc_u32 s91, s9, 0
	v_lshl_add_u64 v[220:221], v[124:125], 0, s[90:91]
	global_load_short_d16_hi v208, v[220:221], off
	global_load_short_d16_hi v209, v[220:221], off offset:2048
	s_add_u32 s90, s8, 0xa003000
	s_addc_u32 s91, s9, 0
	v_lshl_add_u64 v[220:221], v[124:125], 0, s[90:91]
	global_load_short_d16_hi v210, v[220:221], off
	global_load_short_d16_hi v211, v[220:221], off offset:2048
	s_add_u32 s90, s8, 0xa004000
	s_addc_u32 s91, s9, 0
	v_lshl_add_u64 v[220:221], v[124:125], 0, s[90:91]
	global_load_short_d16_hi v212, v[220:221], off
	global_load_short_d16_hi v213, v[220:221], off offset:2048
	s_add_u32 s90, s8, 0xa005000
	s_addc_u32 s91, s9, 0
	v_lshl_add_u64 v[220:221], v[124:125], 0, s[90:91]
	global_load_short_d16_hi v214, v[220:221], off
	global_load_short_d16_hi v215, v[220:221], off offset:2048
	s_add_u32 s90, s8, 0xa006000
	s_addc_u32 s91, s9, 0
	v_lshl_add_u64 v[220:221], v[124:125], 0, s[90:91]
	global_load_short_d16_hi v216, v[220:221], off
	global_load_short_d16_hi v217, v[220:221], off offset:2048
	s_add_u32 s90, s8, 0xa007000
	s_addc_u32 s91, s9, 0
	v_lshl_add_u64 v[220:221], v[124:125], 0, s[90:91]
	global_load_short_d16_hi v218, v[220:221], off
	global_load_short_d16_hi v219, v[220:221], off offset:2048
	v_lshlrev_b64 v[72:73], 11, v[112:113]
	v_lshl_add_u64 v[72:73], v[122:123], 0, v[72:73]
	global_load_dwordx4 v[72:75], v[72:73], off

; #define LAS __attribute__((address_space(3)))
; template <bool PASSB>
; __device__ __forceinline__ void lru_unit(LAS unsigned char* lds, const Params& p, int b, int hd, int chunk) {
;     ...
;         for (int tb = 0; tb < 4; ++tb) {
;             f32x4 ar = (f32x4){0.f, 0.f, 0.f, 0.f}, ai = (f32x4){0.f, 0.f, 0.f, 0.f};
; #pragma unroll
;             for (int ks = 0; ks < 4; ++ks) {
;                 const bf16x8 a = *(const LAS bf16x8*)(XCB + (tb * 16 + fr) * 272 + (ks * 32 + fq * 8) * 2);
;                 ar = __builtin_amdgcn_mfma_f32_16x16x32_bf16(a, wf[0][ks], ar, 0, 0, 0);
;                 ai = __builtin_amdgcn_mfma_f32_16x16x32_bf16(a, wf[1][ks], ai, 0, 0, 0);
;             }
; #pragma unroll
;             for (int j = 0; j < 4; ++j) {
;                 const int token = fq * 16 + tb * 4 + j;
;                 const float xcv = XCF[token * 132 + chl];
;                 const float e1 = __expf(fminf(-(ar[j] + brv), 40.f)), e2 = __expf(fminf(-(ai[j] + biv), 40.f));
;                 const float inv = __builtin_amdgcn_rcpf((1.0f + e1) * (1.0f + e2));
;                 const float r = inv * (1.0f + e2), ig = inv * (1.0f + e1);
;                 const float a = __expf(clv * r);
;                 const float bb = __builtin_amdgcn_sqrtf(fmaxf(1.0f - a * a, 0.f)) * (ig * xcv);
;                 hrun = a * hrun + bb; prun *= a;
.LBB0_615:
	v_add3_u32 v145, s12, v116, v130
	ds_read_b128 v[104:107], v145
	ds_read_b128 v[108:111], v145 offset:64
	ds_read_b128 v[146:149], v145 offset:128
	ds_read_b128 v[150:153], v145 offset:192
	v_lshlrev_b32_e32 v112, 2, v114
	s_waitcnt lgkmcnt(3)
	v_mfma_f32_16x16x32_bf16 v[140:143], v[104:107], v[24:27], 0
	v_mfma_f32_16x16x32_bf16 v[104:107], v[104:107], v[28:31], 0
	s_waitcnt lgkmcnt(2)
	v_mfma_f32_16x16x32_bf16 v[140:143], v[108:111], v[16:19], v[140:143]
	v_mfma_f32_16x16x32_bf16 v[104:107], v[108:111], v[20:23], v[104:107]
	s_waitcnt lgkmcnt(1)
	v_mfma_f32_16x16x32_bf16 v[108:111], v[146:149], v[8:11], v[140:143]
	v_mfma_f32_16x16x32_bf16 v[104:107], v[146:149], v[12:15], v[104:107]
	s_nop 3
	v_add3_u32 v143, s12, v112, v121
	v_add_u32_e32 v127, 0x4400, v143
	s_waitcnt lgkmcnt(0)
	v_mfma_f32_16x16x32_bf16 v[108:111], v[150:153], v[0:3], v[108:111]
	v_mfma_f32_16x16x32_bf16 v[104:107], v[150:153], v[4:7], v[104:107]
	s_nop 6
	v_fma_f32 v108, v108, s72, v200
	v_fma_f32 v104, v104, s72, v201
	v_min_f32_e32 v108, s73, v108
	v_min_f32_e32 v104, s73, v104
	v_exp_f32_e32 v108, v108
	v_exp_f32_e32 v104, v104
	v_fma_f32 v105, v105, s72, v201
	v_min_f32_e32 v105, s73, v105
	v_add_f32_e32 v108, 1.0, v108
	v_add_f32_e32 v129, 1.0, v104
	v_mul_f32_e32 v104, v108, v129
	v_rcp_f32_e32 v140, v104
	v_fma_f32 v109, v109, s72, v200
	v_exp_f32_e32 v128, v105
	ds_read2_b32 v[104:105], v127 offset1:132
	v_mul_f32_e32 v127, v129, v140
	v_min_f32_e32 v109, s73, v109
	v_mul_f32_e32 v127, v202, v127
	v_exp_f32_e32 v109, v109
	v_exp_f32_e32 v127, v127
	v_add_f32_e32 v128, 1.0, v128
	v_mul_f32_e32 v108, v108, v140
	v_add_f32_e32 v109, 1.0, v109
	v_fma_f32 v140, -v127, v127, 1.0 clamp
	v_fma_f32 v110, v110, s72, v200
	v_fma_f32 v106, v106, s72, v201
	v_mul_f32_e32 v129, v109, v128
	v_min_f32_e32 v110, s73, v110
	v_min_f32_e32 v106, s73, v106
	v_rcp_f32_e32 v129, v129
	v_sqrt_f32_e32 v140, v140
	v_exp_f32_e32 v110, v110
	v_exp_f32_e32 v106, v106
	s_waitcnt lgkmcnt(0)
	v_mul_f32_e32 v104, v104, v108
	v_mul_f32_e32 v108, v128, v129
	v_mul_f32_e32 v140, v104, v140
	v_mul_f32_e32 v104, v109, v129
	v_mul_f32_e32 v108, v202, v108
	v_mul_f32_e32 v104, v105, v104
	v_add_f32_e32 v105, 1.0, v110
	v_add_f32_e32 v106, 1.0, v106
	v_mul_f32_e32 v110, v105, v106
	v_exp_f32_e32 v108, v108
	v_rcp_f32_e32 v110, v110
	v_fmac_f32_e32 v140, 0, v127
	v_fma_f32 v109, -v108, v108, 1.0 clamp
	v_mul_f32_e32 v106, v106, v110
	v_mul_f32_e32 v106, v202, v106
	v_sqrt_f32_e32 v109, v109
	v_exp_f32_e32 v158, v106
	v_mul_f32_e32 v141, v108, v140
	v_fmac_f32_e32 v141, v104, v109
	v_add_u32_e32 v104, 0x4800, v143
	ds_read2_b32 v[128:129], v104 offset0:8 offset1:140
	ds_read_b128 v[146:149], v145 offset:4352
	v_fma_f32 v104, -v158, v158, 1.0 clamp
	v_sqrt_f32_e32 v159, v104
	v_fma_f32 v104, v111, s72, v200
	v_min_f32_e32 v104, s73, v104
	v_mul_f32_e32 v142, v127, v108
	v_mul_f32_e32 v144, v105, v110
	ds_read_b128 v[108:111], v145 offset:4416
	v_exp_f32_e32 v154, v104
	v_fma_f32 v104, v107, s72, v201
	v_min_f32_e32 v155, s73, v104
	s_waitcnt lgkmcnt(1)
	v_mfma_f32_16x16x32_bf16 v[150:153], v[146:149], v[24:27], 0
	v_add_f32_e32 v160, 1.0, v154
	v_mul_f32_e32 v128, v128, v144
	v_mul_f32_e32 v144, v158, v141
	v_mfma_f32_16x16x32_bf16 v[104:107], v[146:149], v[28:31], 0
	v_exp_f32_e32 v155, v155
	ds_read_b128 v[146:149], v145 offset:4480
	s_waitcnt lgkmcnt(1)
	v_mfma_f32_16x16x32_bf16 v[150:153], v[108:111], v[16:19], v[150:153]
	v_fmac_f32_e32 v144, v128, v159
	v_add_f32_e32 v161, 1.0, v155
	ds_read_b128 v[154:157], v145 offset:4544
	v_mfma_f32_16x16x32_bf16 v[104:107], v[108:111], v[20:23], v[104:107]
	v_mul_f32_e32 v108, v160, v161
	v_rcp_f32_e32 v162, v108
	s_waitcnt lgkmcnt(1)
	v_mfma_f32_16x16x32_bf16 v[108:111], v[146:149], v[8:11], v[150:153]
	v_mul_f32_e32 v128, v161, v162
	v_mul_f32_e32 v128, v202, v128
	v_mfma_f32_16x16x32_bf16 v[104:107], v[146:149], v[12:15], v[104:107]
	v_exp_f32_e32 v128, v128
	v_mul_f32_e32 v147, v160, v162
	s_waitcnt lgkmcnt(0)
	v_mfma_f32_16x16x32_bf16 v[108:111], v[154:157], v[0:3], v[108:111]
	v_mul_f32_e32 v146, v158, v142
	v_fma_f32 v148, -v128, v128, 1.0 clamp
	v_mfma_f32_16x16x32_bf16 v[104:107], v[154:157], v[4:7], v[104:107]
	v_sqrt_f32_e32 v148, v148
	s_nop 2
	s_nop 0
	v_fma_f32 v108, v108, s72, v200
	v_min_f32_e32 v108, s73, v108
	v_exp_f32_e32 v108, v108
	v_fma_f32 v104, v104, s72, v201
	v_min_f32_e32 v104, s73, v104
	v_exp_f32_e32 v104, v104
	v_add_f32_e32 v108, 1.0, v108
	v_fma_f32 v109, v109, s72, v200
	v_fma_f32 v105, v105, s72, v201
	v_add_f32_e32 v104, 1.0, v104
	v_mul_f32_e32 v149, v108, v104
	v_rcp_f32_e32 v149, v149
	v_min_f32_e32 v109, s73, v109
	v_min_f32_e32 v105, s73, v105
	v_mul_f32_e32 v104, v104, v149
	v_mul_f32_e32 v104, v202, v104
	v_exp_f32_e32 v104, v104
	v_exp_f32_e32 v109, v109
	v_exp_f32_e32 v105, v105
	v_mul_f32_e32 v129, v129, v147
	v_mul_f32_e32 v147, v128, v144
	v_fmac_f32_e32 v147, v129, v148
	v_mul_f32_e32 v148, v128, v146
	v_add_u32_e32 v128, 0x4c00, v143
	ds_read2_b32 v[128:129], v128 offset0:16 offset1:148
	v_fma_f32 v150, -v104, v104, 1.0 clamp
	v_add_f32_e32 v109, 1.0, v109
	v_add_f32_e32 v105, 1.0, v105
	v_sqrt_f32_e32 v150, v150
	v_mul_f32_e32 v151, v109, v105
	v_rcp_f32_e32 v151, v151
	v_mul_f32_e32 v108, v108, v149
	s_waitcnt lgkmcnt(0)
; #define LAS __attribute__((address_space(3)))
; template <bool PASSB>
; __device__ __forceinline__ void lru_unit(LAS unsigned char* lds, const Params& p, int b, int hd, int chunk) {
;     ...
;         for (int tb = 0; tb < 4; ++tb) {
;             f32x4 ar = (f32x4){0.f, 0.f, 0.f, 0.f}, ai = (f32x4){0.f, 0.f, 0.f, 0.f};
; #pragma unroll
;             for (int ks = 0; ks < 4; ++ks) {
;                 const bf16x8 a = *(const LAS bf16x8*)(XCB + (tb * 16 + fr) * 272 + (ks * 32 + fq * 8) * 2);
;                 ar = __builtin_amdgcn_mfma_f32_16x16x32_bf16(a, wf[0][ks], ar, 0, 0, 0);
;                 ai = __builtin_amdgcn_mfma_f32_16x16x32_bf16(a, wf[1][ks], ai, 0, 0, 0);
;             }
; #pragma unroll
;             for (int j = 0; j < 4; ++j) {
;                 const int token = fq * 16 + tb * 4 + j;
;                 const float xcv = XCF[token * 132 + chl];
;                 const float e1 = __expf(fminf(-(ar[j] + brv), 40.f)), e2 = __expf(fminf(-(ai[j] + biv), 40.f));
;                 const float inv = __builtin_amdgcn_rcpf((1.0f + e1) * (1.0f + e2));
;                 const float r = inv * (1.0f + e2), ig = inv * (1.0f + e1);
;                 const float a = __expf(clv * r);
;                 const float bb = __builtin_amdgcn_sqrtf(fmaxf(1.0f - a * a, 0.f)) * (ig * xcv);
;                 hrun = a * hrun + bb; prun *= a;
;                 if (PASSB) { hl[tb * 4 + j] = hrun; pl[tb * 4 + j] = prun; }
;             }
	v_mul_f32_e32 v108, v128, v108
	v_mul_f32_e32 v149, v108, v150
	v_fmac_f32_e32 v149, v147, v104
	v_mul_f32_e32 v150, v148, v104
	v_mul_f32_e32 v104, v109, v151
	v_fma_f32 v109, v110, s72, v200
	v_fma_f32 v106, v106, s72, v201
	v_min_f32_e32 v109, s73, v109
	v_min_f32_e32 v106, s73, v106
	v_exp_f32_e32 v109, v109
	v_exp_f32_e32 v106, v106
	v_mul_f32_e32 v105, v105, v151
	v_mul_f32_e32 v105, v202, v105
	v_add_f32_e32 v109, 1.0, v109
	v_add_f32_e32 v106, 1.0, v106
	v_mul_f32_e32 v110, v109, v106
	v_exp_f32_e32 v105, v105
	v_rcp_f32_e32 v110, v110
	v_mul_f32_e32 v104, v129, v104
	v_fma_f32 v108, -v105, v105, 1.0 clamp
	v_mul_f32_e32 v151, v105, v149
	v_mul_f32_e32 v152, v105, v150
	v_mul_f32_e32 v105, v106, v110
	v_mul_f32_e32 v105, v202, v105
	v_sqrt_f32_e32 v108, v108
	v_exp_f32_e32 v153, v105
	v_mul_f32_e32 v162, v109, v110
	v_fmac_f32_e32 v151, v104, v108
	v_add_u32_e32 v104, 0x5000, v143
	ds_read2_b32 v[128:129], v104 offset0:24 offset1:156
	ds_read_b128 v[154:157], v145 offset:8704
	v_fma_f32 v104, -v153, v153, 1.0 clamp
	v_sqrt_f32_e32 v166, v104
	v_fma_f32 v104, v111, s72, v200
	v_min_f32_e32 v104, s73, v104
	ds_read_b128 v[108:111], v145 offset:8768
	v_exp_f32_e32 v163, v104
	v_fma_f32 v104, v107, s72, v201
	v_min_f32_e32 v164, s73, v104
	s_waitcnt lgkmcnt(1)
	v_mfma_f32_16x16x32_bf16 v[158:161], v[154:157], v[24:27], 0
	v_mul_f32_e32 v167, v128, v162
	v_add_f32_e32 v168, 1.0, v163
	v_mul_f32_e32 v128, v153, v151
	v_mfma_f32_16x16x32_bf16 v[104:107], v[154:157], v[28:31], 0
	v_exp_f32_e32 v164, v164
	ds_read_b128 v[154:157], v145 offset:8832
	s_waitcnt lgkmcnt(1)
	v_mfma_f32_16x16x32_bf16 v[158:161], v[108:111], v[16:19], v[158:161]
	v_fmac_f32_e32 v128, v167, v166
	v_add_f32_e32 v169, 1.0, v164
	ds_read_b128 v[162:165], v145 offset:8896
	v_mfma_f32_16x16x32_bf16 v[104:107], v[108:111], v[20:23], v[104:107]
	v_mul_f32_e32 v108, v168, v169
	v_rcp_f32_e32 v171, v108
	v_mul_f32_e32 v153, v153, v152
	s_waitcnt lgkmcnt(1)
	v_mfma_f32_16x16x32_bf16 v[108:111], v[154:157], v[8:11], v[158:161]
	v_mfma_f32_16x16x32_bf16 v[104:107], v[154:157], v[12:15], v[104:107]
	s_nop 1
	v_mul_f32_e32 v158, v169, v171
	v_mul_f32_e32 v154, v202, v158
	s_waitcnt lgkmcnt(0)
	v_mfma_f32_16x16x32_bf16 v[108:111], v[162:165], v[0:3], v[108:111]
	v_exp_f32_e32 v154, v154
	v_mul_f32_e32 v155, v168, v171
	v_mul_f32_e32 v155, v129, v155
	v_mfma_f32_16x16x32_bf16 v[104:107], v[162:165], v[4:7], v[104:107]
	v_fma_f32 v156, -v154, v154, 1.0 clamp
	s_nop 2
	v_fma_f32 v108, v108, s72, v200
	v_min_f32_e32 v108, s73, v108
	v_exp_f32_e32 v108, v108
	s_nop 0
	v_fma_f32 v104, v104, s72, v201
	v_min_f32_e32 v104, s73, v104
	v_exp_f32_e32 v104, v104
	v_add_f32_e32 v108, 1.0, v108
	v_fma_f32 v109, v109, s72, v200
	v_fma_f32 v105, v105, s72, v201
	v_add_f32_e32 v104, 1.0, v104
	v_mul_f32_e32 v157, v108, v104
	v_rcp_f32_e32 v158, v157
	v_min_f32_e32 v109, s73, v109
	v_min_f32_e32 v105, s73, v105
	v_mul_f32_e32 v104, v104, v158
	v_exp_f32_e32 v109, v109
	v_exp_f32_e32 v105, v105
	v_sqrt_f32_e32 v156, v156
	v_mul_f32_e32 v104, v202, v104
	v_exp_f32_e32 v104, v104
	v_mul_f32_e32 v129, v154, v128
	v_add_f32_e32 v159, 1.0, v109
	v_add_f32_e32 v105, 1.0, v105
	v_fmac_f32_e32 v129, v155, v156
	v_add_u32_e32 v155, 0x5400, v143
	v_mul_f32_e32 v109, v159, v105
	ds_read2_b32 v[156:157], v155 offset0:32 offset1:164
	v_rcp_f32_e32 v160, v109
	v_fma_f32 v155, -v104, v104, 1.0 clamp
	v_fma_f32 v110, v110, s72, v200
	v_fma_f32 v106, v106, s72, v201
	v_sqrt_f32_e32 v155, v155
	v_min_f32_e32 v110, s73, v110
	v_min_f32_e32 v106, s73, v106
	v_mul_f32_e32 v108, v108, v158
	v_mul_f32_e32 v105, v105, v160
	s_waitcnt lgkmcnt(0)
	v_mul_f32_e32 v108, v156, v108
	v_mul_f32_e32 v105, v202, v105
	v_exp_f32_e32 v156, v110
	v_exp_f32_e32 v106, v106
	v_mul_f32_e32 v154, v154, v153
	v_mul_f32_e32 v109, v108, v155
	v_exp_f32_e32 v105, v105
	v_fmac_f32_e32 v109, v129, v104
	v_mul_f32_e32 v155, v154, v104
	v_mul_f32_e32 v104, v159, v160
	v_mul_f32_e32 v104, v157, v104
	v_add_f32_e32 v157, 1.0, v156
	v_add_f32_e32 v106, 1.0, v106
	v_mul_f32_e32 v156, v157, v106
	v_fma_f32 v108, -v105, v105, 1.0 clamp
	v_rcp_f32_e32 v162, v156
	v_sqrt_f32_e32 v108, v108
	v_mul_f32_e32 v110, v105, v109
	v_mul_f32_e32 v156, v105, v155
	v_mul_f32_e32 v105, v106, v162
	v_mul_f32_e32 v105, v202, v105
	v_fmac_f32_e32 v110, v104, v108
	v_add_u32_e32 v104, 0x5800, v143
	v_exp_f32_e32 v106, v105
	ds_read2_b32 v[104:105], v104 offset0:40 offset1:172
	ds_read_b128 v[158:161], v145 offset:13056
	v_mul_f32_e32 v108, v157, v162
	ds_read_b128 v[162:165], v145 offset:13120
	ds_read_b128 v[172:175], v145 offset:13184
	s_waitcnt lgkmcnt(2)
	v_mfma_f32_16x16x32_bf16 v[166:169], v[158:161], v[24:27], 0
	v_fma_f32 v111, v111, s72, v200
	v_fma_f32 v107, v107, s72, v201
	v_min_f32_e32 v111, s73, v111
	v_mfma_f32_16x16x32_bf16 v[158:161], v[158:161], v[28:31], 0
	v_min_f32_e32 v107, s73, v107
	s_waitcnt lgkmcnt(1)
	v_mfma_f32_16x16x32_bf16 v[166:169], v[162:165], v[16:19], v[166:169]
	v_exp_f32_e32 v111, v111
	v_exp_f32_e32 v107, v107
	v_fma_f32 v157, -v106, v106, 1.0 clamp
	v_mfma_f32_16x16x32_bf16 v[158:161], v[162:165], v[20:23], v[158:161]
	ds_read_b128 v[162:165], v145 offset:13248
	v_mul_f32_e32 v104, v104, v108
	v_add_f32_e32 v108, 1.0, v111
	s_waitcnt lgkmcnt(1)
	v_mfma_f32_16x16x32_bf16 v[166:169], v[172:175], v[8:11], v[166:169]
	v_add_f32_e32 v107, 1.0, v107
	v_mul_f32_e32 v111, v108, v107
	v_mfma_f32_16x16x32_bf16 v[158:161], v[172:175], v[12:15], v[158:161]
	v_sqrt_f32_e32 v157, v157
	v_rcp_f32_e32 v171, v111
	v_mul_f32_e32 v111, v106, v110
	s_waitcnt lgkmcnt(0)
; template <bool PASSB>
; __device__ __forceinline__ void lru_unit(LAS unsigned char* lds, const Params& p, int b, int hd, int chunk) {
;     ...
;             for (int j = 0; j < 4; ++j) {
;                 const int token = fq * 16 + tb * 4 + j;
;                 const float xcv = XCF[token * 132 + chl];
;                 const float e1 = __expf(fminf(-(ar[j] + brv), 40.f)), e2 = __expf(fminf(-(ai[j] + biv), 40.f));
;                 const float inv = __builtin_amdgcn_rcpf((1.0f + e1) * (1.0f + e2));
;                 const float r = inv * (1.0f + e2), ig = inv * (1.0f + e1);
;                 const float a = __expf(clv * r);
;                 const float bb = __builtin_amdgcn_sqrtf(fmaxf(1.0f - a * a, 0.f)) * (ig * xcv);
;                 hrun = a * hrun + bb; prun *= a;
;                 if (PASSB) { hl[tb * 4 + j] = hrun; pl[tb * 4 + j] = prun; }
;             }
;         }
;         const float P0 = __shfl(prun, fr), H0 = __shfl(hrun, fr), P1 = __shfl(prun, fr + 16), H1 = __shfl(hrun, fr + 16);
;         const float P2 = __shfl(prun, fr + 32), H2 = __shfl(hrun, fr + 32), P3 = __shfl(prun, fr + 48), H3 = __shfl(hrun, fr + 48);
;         const float s0 = P0 * Cst + H0, s1 = P1 * s0 + H1, s2 = P2 * s1 + H2, s3 = P3 * s2 + H3;
;         const float cin = fq == 0 ? Cst : (fq == 1 ? s0 : (fq == 2 ? s1 : s2));
	v_mfma_f32_16x16x32_bf16 v[166:169], v[162:165], v[0:3], v[166:169]
	v_fmac_f32_e32 v111, v104, v157
	v_mul_f32_e32 v104, v107, v171
	v_mul_f32_e32 v145, v106, v156
	v_mfma_f32_16x16x32_bf16 v[160:163], v[162:165], v[4:7], v[158:161]
	v_mul_f32_e32 v106, v108, v171
	s_nop 2
	v_fma_f32 v108, v166, s72, v200
	v_mul_f32_e32 v104, v202, v104
	v_min_f32_e32 v108, s73, v108
	s_nop 0
	v_fma_f32 v157, v160, s72, v201
	v_min_f32_e32 v157, s73, v157
	v_exp_f32_e32 v104, v104
	v_exp_f32_e32 v108, v108
	v_exp_f32_e32 v157, v157
	v_mul_f32_e32 v105, v105, v106
	v_fma_f32 v107, -v104, v104, 1.0 clamp
	v_add_f32_e32 v108, 1.0, v108
	v_add_f32_e32 v158, 1.0, v157
	v_mul_f32_e32 v157, v108, v158
	v_sqrt_f32_e32 v107, v107
	v_rcp_f32_e32 v159, v157
	v_mul_f32_e32 v157, v104, v111
	v_fma_f32 v160, v167, s72, v200
	v_fmac_f32_e32 v157, v105, v107
	v_mul_f32_e32 v105, v158, v159
	v_fma_f32 v161, v161, s72, v201
	v_mul_f32_e32 v105, v202, v105
	v_min_f32_e32 v160, s73, v160
	v_min_f32_e32 v161, s73, v161
	v_exp_f32_e32 v106, v105
	v_exp_f32_e32 v160, v160
	v_exp_f32_e32 v161, v161
	v_mul_f32_e32 v158, v104, v145
	v_add_u32_e32 v104, 0x5c00, v143
	ds_read2_b32 v[104:105], v104 offset0:48 offset1:180
	v_fma_f32 v107, -v106, v106, 1.0 clamp
	v_add_f32_e32 v164, 1.0, v160
	v_add_f32_e32 v160, 1.0, v161
	v_mul_f32_e32 v161, v164, v160
	v_sqrt_f32_e32 v107, v107
	v_rcp_f32_e32 v161, v161
	v_mul_f32_e32 v108, v108, v159
	s_waitcnt lgkmcnt(0)
	v_mul_f32_e32 v104, v104, v108
	v_mul_f32_e32 v159, v104, v107
	v_mul_f32_e32 v104, v160, v161
	v_mul_f32_e32 v104, v202, v104
	v_exp_f32_e32 v104, v104
	v_fmac_f32_e32 v159, v157, v106
	v_mul_f32_e32 v160, v158, v106
	v_mul_f32_e32 v106, v164, v161
	v_mul_f32_e32 v105, v105, v106
	v_fma_f32 v106, v168, s72, v200
	v_fma_f32 v108, v162, s72, v201
	v_fma_f32 v107, -v104, v104, 1.0 clamp
	v_min_f32_e32 v106, s73, v106
	v_min_f32_e32 v108, s73, v108
	v_sqrt_f32_e32 v107, v107
	v_exp_f32_e32 v106, v106
	v_exp_f32_e32 v108, v108
	v_mul_f32_e32 v161, v104, v159
	v_mul_f32_e32 v162, v104, v160
	v_add_u32_e32 v104, 0x6000, v143
	v_fma_f32 v143, v169, s72, v200
	v_fma_f32 v163, v163, s72, v201
	v_fmac_f32_e32 v161, v105, v107
	v_add_f32_e32 v106, 1.0, v106
	v_add_f32_e32 v107, 1.0, v108
	v_min_f32_e32 v143, s73, v143
	v_min_f32_e32 v163, s73, v163
	v_mul_f32_e32 v105, v106, v107
	v_rcp_f32_e32 v108, v105
	v_exp_f32_e32 v143, v143
	v_exp_f32_e32 v163, v163
	ds_read2_b32 v[104:105], v104 offset0:56 offset1:188
	v_mul_f32_e32 v107, v107, v108
	v_add_f32_e32 v164, 1.0, v143
	v_add_f32_e32 v143, 1.0, v163
	v_mul_f32_e32 v107, v202, v107
	v_mul_f32_e32 v163, v164, v143
	v_rcp_f32_e32 v165, v163
	v_exp_f32_e32 v107, v107
	v_mul_f32_e32 v106, v106, v108
	s_waitcnt lgkmcnt(0)
	v_mul_f32_e32 v104, v104, v106
	v_mul_f32_e32 v106, v143, v165
	v_fma_f32 v108, -v107, v107, 1.0 clamp
	v_mul_f32_e32 v106, v202, v106
	v_sqrt_f32_e32 v108, v108
	v_exp_f32_e32 v106, v106
	v_mul_f32_e32 v143, v107, v161
	v_mul_f32_e32 v163, v107, v162
	v_fmac_f32_e32 v143, v104, v108
	v_fma_f32 v104, -v106, v106, 1.0 clamp
	v_sqrt_f32_e32 v104, v104
	v_mul_f32_e32 v107, v164, v165
	v_mul_f32_e32 v105, v105, v107
	v_mul_f32_e32 v164, v106, v143
	v_fmac_f32_e32 v164, v105, v104
	v_lshl_add_u64 v[104:105], v[124:125], 0, s[8:9]
	v_mul_f32_e32 v165, v106, v163
	ds_bpermute_b32 v185, v117, v165
	ds_bpermute_b32 v176, v117, v164
	ds_bpermute_b32 v187, v117, v165 offset:64
	ds_bpermute_b32 v182, v117, v164 offset:64
	ds_bpermute_b32 v188, v117, v165 offset:128
	ds_bpermute_b32 v174, v117, v164 offset:128
	ds_bpermute_b32 v175, v117, v165 offset:192
	ds_bpermute_b32 v106, v117, v164 offset:192
	s_waitcnt lgkmcnt(6)
	v_fmac_f32_e32 v176, v137, v185
	s_waitcnt lgkmcnt(4)
	v_fmac_f32_e32 v182, v176, v187
	v_or_b32_e32 v108, 64, v117
	v_or_b32_e32 v107, 0x80, v117
	s_waitcnt lgkmcnt(2)
	v_fmac_f32_e32 v174, v182, v188
	v_cmp_lt_i32_e32 vcc, 0, v135
	s_and_saveexec_b64 s[10:11], vcc
	s_cbranch_execz .LBB0_621
	v_cmp_ne_u32_e32 vcc, 1, v135
	s_and_saveexec_b64 s[12:13], vcc
	s_xor_b64 s[12:13], exec, s[12:13]
	v_cndmask_b32_e64 v137, v174, v182, s[0:1]
	s_andn2_saveexec_b64 s[12:13], s[12:13]
	v_mov_b32_e32 v137, v176
	s_or_b64 exec, exec, s[12:13]
; __device__ __forceinline__ unsigned cvt_pk_bf16(float lo, float hi) { unsigned r; asm volatile("v_cvt_pk_bf16_f32 %0, %1, %2" : "=v"(r) : "v"(lo), "v"(hi)); return r; }
; template <bool PASSB>
; __device__ __forceinline__ void lru_unit(LAS unsigned char* lds, const Params& p, int b, int hd, int chunk) {
;     ...
;         if (PASSB) {
; #pragma unroll
;             for (int q = 0; q < 16; ++q) {
;                 const float hv = hl[q] + pl[q] * cin;
;                 const float gt = __uint_as_float(((unsigned)gvv[q]) << 16);
;                 YA[obase + (size_t)q * 1024] = (bf16_t)(cvt_pk_bf16(hv * gt, 0.f) & 0xffffu);
;             }
.LBB0_621:
	s_or_b64 exec, exec, s[10:11]
	v_fmac_f32_e32 v140, v127, v137
	s_waitcnt vmcnt(15)
	s_waitcnt lgkmcnt(0)
	v_fmac_f32_e32 v106, v174, v175
	v_mul_f32_e32 v127, v140, v204
	v_lshl_add_u64 v[222:223], v[104:105], 0, s[86:87]
	v_cvt_pk_bf16_f32 v127, v127, v113
	v_fmac_f32_e32 v141, v142, v137
	global_store_short v[222:223], v127, off
	s_waitcnt vmcnt(15)
	v_mul_f32_e32 v127, v141, v205
	v_cvt_pk_bf16_f32 v127, v127, v113
	global_store_short v[222:223], v127, off offset:2048
	v_fmac_f32_e32 v144, v146, v137
	s_waitcnt vmcnt(15)
	v_mul_f32_e32 v127, v144, v206
	v_lshl_add_u64 v[222:223], v[222:223], 0, s[88:89]
	v_cvt_pk_bf16_f32 v127, v127, v113
	v_fmac_f32_e32 v147, v148, v137
	global_store_short v[222:223], v127, off
	s_waitcnt vmcnt(15)
	v_mul_f32_e32 v127, v147, v207
	v_cvt_pk_bf16_f32 v127, v127, v113
	global_store_short v[222:223], v127, off offset:2048
	v_fmac_f32_e32 v149, v150, v137
	s_waitcnt vmcnt(15)
	v_mul_f32_e32 v127, v149, v208
	v_lshl_add_u64 v[222:223], v[222:223], 0, s[88:89]
	v_cvt_pk_bf16_f32 v127, v127, v113
	v_fmac_f32_e32 v151, v152, v137
	global_store_short v[222:223], v127, off
	s_waitcnt vmcnt(15)
	v_mul_f32_e32 v127, v151, v209
	v_cvt_pk_bf16_f32 v127, v127, v113
	global_store_short v[222:223], v127, off offset:2048
	v_fmac_f32_e32 v128, v153, v137
	s_waitcnt vmcnt(15)
	v_mul_f32_e32 v127, v128, v210
	v_lshl_add_u64 v[222:223], v[222:223], 0, s[88:89]
	v_cvt_pk_bf16_f32 v127, v127, v113
	v_fmac_f32_e32 v129, v154, v137
	global_store_short v[222:223], v127, off
	s_waitcnt vmcnt(15)
	v_mul_f32_e32 v127, v129, v211
	v_cvt_pk_bf16_f32 v127, v127, v113
	global_store_short v[222:223], v127, off offset:2048
	v_fmac_f32_e32 v109, v155, v137
	s_waitcnt vmcnt(15)
	v_mul_f32_e32 v109, v109, v212
	v_lshl_add_u64 v[222:223], v[222:223], 0, s[88:89]
	v_cvt_pk_bf16_f32 v109, v109, v113
	v_fmac_f32_e32 v110, v156, v137
	global_store_short v[222:223], v109, off
	s_waitcnt vmcnt(15)
	v_mul_f32_e32 v109, v110, v213
	v_cvt_pk_bf16_f32 v109, v109, v113
	global_store_short v[222:223], v109, off offset:2048
	v_fmac_f32_e32 v111, v145, v137
	s_waitcnt vmcnt(15)
	v_mul_f32_e32 v109, v111, v214
	v_lshl_add_u64 v[222:223], v[222:223], 0, s[88:89]
	v_cvt_pk_bf16_f32 v109, v109, v113
	v_fmac_f32_e32 v157, v158, v137
	global_store_short v[222:223], v109, off
	s_waitcnt vmcnt(15)
	v_mul_f32_e32 v109, v157, v215
	v_cvt_pk_bf16_f32 v109, v109, v113
	global_store_short v[222:223], v109, off offset:2048
	v_fmac_f32_e32 v159, v160, v137
	s_waitcnt vmcnt(15)
	v_mul_f32_e32 v109, v159, v216
	v_lshl_add_u64 v[222:223], v[222:223], 0, s[88:89]
	v_cvt_pk_bf16_f32 v109, v109, v113
	v_fmac_f32_e32 v161, v162, v137
	global_store_short v[222:223], v109, off
	s_waitcnt vmcnt(15)
	v_mul_f32_e32 v109, v161, v217
	v_cvt_pk_bf16_f32 v109, v109, v113
	global_store_short v[222:223], v109, off offset:2048
	v_fmac_f32_e32 v143, v163, v137
	s_waitcnt vmcnt(15)
	v_mul_f32_e32 v109, v143, v218
	v_lshl_add_u64 v[222:223], v[222:223], 0, s[88:89]
	v_cvt_pk_bf16_f32 v109, v109, v113
	s_add_u32 s8, s8, 0x20000
	global_store_short v[222:223], v109, off
	v_fmac_f32_e32 v164, v165, v137
	s_waitcnt vmcnt(15)
	s_addc_u32 s9, s9, 0
	s_add_i32 s14, s14, 1
	v_mul_f32_e32 v109, v164, v219
	s_cmp_eq_u32 s8, 0x1e0000
	v_add_u32_e32 v126, 64, v126
	v_cvt_pk_bf16_f32 v109, v109, v113
	global_store_short v[222:223], v109, off offset:2048
	s_cbranch_scc1 .LBB0_623
	v_mov_b32_e32 v137, v106
	s_branch .LBB0_599

; template <bool PASSB>
; __device__ __forceinline__ void s5_phase(LAS unsigned char* lds, const Params& p) {
;     ...
;         const size_t row0 = (size_t)b * SEQ + (size_t)c * S5_LC;
;         const bf16_t* up = U + ((size_t)g * T + row0 + fr) * 16 + (fq & 1) * 8;
;         bf16x8 au_q0 = (fq < 2) ? *(const bf16x8*)up : zero8;
;         bf16x8 au_q1 = (fq < 2) ? *(const bf16x8*)(up + (size_t)1 * 16 * 16) : zero8;
;         bf16x8 au_q2 = (fq < 2) ? *(const bf16x8*)(up + (size_t)2 * 16 * 16) : zero8;
.LBB0_1092:
	s_or_b64 exec, exec, s[24:25]
	v_and_b32_e32 v1, 63, v105
	v_lshl_or_b32 v98, v1, 15, v72
	v_mov_b32_e32 v99, v73
	v_lshl_add_u64 v[64:65], v[98:99], 0, v[64:65]
	v_lshl_add_u64 v[64:65], v[64:65], 0, v[66:67]
	v_lshlrev_b32_e32 v2, 5, v93
	v_mov_b32_e32 v3, v0
	v_lshlrev_b64 v[64:65], 5, v[64:65]
	v_lshl_add_u64 v[2:3], v[82:83], 0, v[2:3]
	v_mov_b32_e32 v89, v88
	v_mov_b32_e32 v93, v92
	v_lshl_add_u64 v[98:99], v[84:85], 0, v[64:65]
	s_mov_b32 s23, 0
	v_mov_b64_e32 v[100:101], v[86:87]
	v_or_b32_e32 v145, v97, v101
	v_or_b32_e32 v144, v96, v100
	v_lshlrev_b64 v[144:145], 11, v[144:145]
	s_mov_b64 s[80:81], 0x1000
	v_lshl_add_u64 v[144:145], v[2:3], 0, v[144:145]
	v_lshl_add_u64 v[146:147], v[144:145], 0, s[80:81]
	s_mov_b64 s[82:83], 0x8000
	v_add_u32_e32 v158, 0x2800, v109
	v_add_u32_e32 v159, 0x2c40, v109
	v_add_u32_e32 v160, 0x3080, v109
	v_add_u32_e32 v161, 0x34c0, v109
	s_waitcnt vmcnt(0)
	s_branch .LBB0_1094

; template <bool PASSB>
; __device__ __forceinline__ void s5_phase(LAS unsigned char* lds, const Params& p) {
;     ...
;         for (int st = 0; st < NST; ++st) {
;             const size_t r0 = row0 + st * 16;
;             const bf16x8 au = au_q0; au_q0 = au_q1; au_q1 = au_q2;
;             if (st + 3 < NST) au_q2 = (fq < 2) ? *(const bf16x8*)(up + (size_t)(st + 3) * 16 * 16) : zero8;
.LBB0_1094:
	s_waitcnt vmcnt(4)
	v_mov_b64_e32 v[66:67], v[58:59]
	v_mov_b64_e32 v[64:65], v[56:57]
	v_mov_b64_e32 v[56:57], v[60:61]
	s_cmp_gt_u32 s23, 28
	v_mov_b64_e32 v[58:59], v[62:63]
	s_cselect_b64 s[24:25], -1, 0
	v_cndmask_b32_e64 v63, 0, v59, s[24:25]
	s_nor_b64 s[28:29], s[0:1], s[24:25]
	v_cndmask_b32_e64 v62, 0, v58, s[24:25]
	v_cndmask_b32_e64 v61, 0, v57, s[24:25]
	v_cndmask_b32_e64 v60, 0, v56, s[24:25]
	s_and_saveexec_b64 s[24:25], s[28:29]
	s_cbranch_execz .LBB0_1093
	global_load_dwordx4 v[60:63], v[98:99], off nt
	s_branch .LBB0_1093
